# stagger only: workgroups without a tail piece start residual GEMM phases late
# speedup vs baseline: 1.0056x; 1.0056x over previous
;     __host__ __device__ bool next(int i, Unit& u) const {
;         u.kt0 = 0; u.nkt = nkt; u.sliced = 0; u.ha = -1; u.hb = -1;
;         if (mode == 0 || i < rounds) { const long L = (long)i * G + c; if (L >= nwg) return false; tile((int)L, u); return true; }
;         if (i > rounds || c >= left * mode) return false;
;         int t, piece;
;         if ((left & 7) == 0) { const int q = c >> 3, x = c & 7; t = x + 8 * (q / mode); piece = q % mode; } else { t = c / mode; piece = c % mode; }
;         tile(rounds * G + t, u); u.ha = piece & 1; u.hb = (mode == 4) ? (piece >> 1) : -1; return true;
.LBB0_816:
	s_cmp_eq_u32 s56, 0
	s_cbranch_scc1 .Lstag_done
	s_mul_i32 s98, s56, s12
	v_readlane_b32 s99, v254, 0
	s_nop 3
	s_cmp_lt_i32 s99, s98
	s_cbranch_scc1 .Lstag_done
	s_mul_i32 s100, s3, 23
	s_lshr_b32 s100, s100, 5
	s_memrealtime s[98:99]
	s_waitcnt lgkmcnt(0)
	s_add_u32 s99, s98, s100
.Lstag_spin:
	s_memrealtime s[100:101]
	s_waitcnt lgkmcnt(0)
	s_sub_u32 s98, s100, s99
	s_cmp_lt_i32 s98, 0
	s_cbranch_scc1 .Lstag_spin

; __global__ void __launch_bounds__(NTHREADS, 2) fwd_megakernel(Args a) {
	.amdhsa_kernel _Z14fwd_megakernel4Args
		.amdhsa_group_segment_fixed_size 0
		.amdhsa_private_segment_fixed_size 0
		.amdhsa_kernarg_size 408
		.amdhsa_user_sgpr_count 2
		.amdhsa_user_sgpr_dispatch_ptr 0
		.amdhsa_user_sgpr_queue_ptr 0
		.amdhsa_user_sgpr_kernarg_segment_ptr 1
		.amdhsa_user_sgpr_dispatch_id 0
		.amdhsa_user_sgpr_kernarg_preload_length 0
		.amdhsa_user_sgpr_kernarg_preload_offset 0
		.amdhsa_user_sgpr_private_segment_size 0
		.amdhsa_uses_dynamic_stack 0
		.amdhsa_enable_private_segment 0
		.amdhsa_system_sgpr_workgroup_id_x 1
		.amdhsa_system_sgpr_workgroup_id_y 0
		.amdhsa_system_sgpr_workgroup_id_z 0
		.amdhsa_system_sgpr_workgroup_info 0
		.amdhsa_system_vgpr_workitem_id 2
		.amdhsa_next_free_vgpr 256
		.amdhsa_next_free_sgpr 102
		.amdhsa_accum_offset 256
		.amdhsa_reserve_vcc 1
		.amdhsa_float_round_mode_32 0
		.amdhsa_float_round_mode_16_64 0
		.amdhsa_float_denorm_mode_32 3
		.amdhsa_float_denorm_mode_16_64 3
		.amdhsa_dx10_clamp 1
		.amdhsa_ieee_mode 1
		.amdhsa_fp16_overflow 0
		.amdhsa_tg_split 0
		.amdhsa_exception_fp_ieee_invalid_op 0
		.amdhsa_exception_fp_denorm_src 0
		.amdhsa_exception_fp_ieee_div_zero 0
		.amdhsa_exception_fp_ieee_overflow 0
		.amdhsa_exception_fp_ieee_underflow 0
		.amdhsa_exception_fp_ieee_inexact 0
		.amdhsa_exception_int_div_zero 0
	.end_amdhsa_kernel

; __global__ void __launch_bounds__(NTHREADS, 2) fwd_megakernel(Args a) {
amdhsa.kernels:
  - .agpr_count:     0
    .args:
      - .offset:         0
        .size:           152
        .value_kind:     by_value
      - .offset:         152
        .size:           4
        .value_kind:     hidden_block_count_x
      - .offset:         156
        .size:           4
        .value_kind:     hidden_block_count_y
      - .offset:         160
        .size:           4
        .value_kind:     hidden_block_count_z
      - .offset:         164
        .size:           2
        .value_kind:     hidden_group_size_x
      - .offset:         166
        .size:           2
        .value_kind:     hidden_group_size_y
      - .offset:         168
        .size:           2
        .value_kind:     hidden_group_size_z
      - .offset:         170
        .size:           2
        .value_kind:     hidden_remainder_x
      - .offset:         172
        .size:           2
        .value_kind:     hidden_remainder_y
      - .offset:         174
        .size:           2
        .value_kind:     hidden_remainder_z
      - .offset:         192
        .size:           8
        .value_kind:     hidden_global_offset_x
      - .offset:         200
        .size:           8
        .value_kind:     hidden_global_offset_y
      - .offset:         208
        .size:           8
        .value_kind:     hidden_global_offset_z
      - .offset:         216
        .size:           2
        .value_kind:     hidden_grid_dims
      - .offset:         240
        .size:           8
        .value_kind:     hidden_multigrid_sync_arg
      - .offset:         272
        .size:           4
        .value_kind:     hidden_dynamic_lds_size
    .group_segment_fixed_size: 0
    .kernarg_segment_align: 8
    .kernarg_segment_size: 408
    .language:       OpenCL C
    .language_version:
      - 2
      - 0
    .max_flat_workgroup_size: 512
    .name:           _Z14fwd_megakernel4Args
    .private_segment_fixed_size: 0
    .sgpr_count:     108
    .sgpr_spill_count: 106
    .symbol:         _Z14fwd_megakernel4Args.kd
    .uniform_work_group_size: 1
    .uses_dynamic_stack: false
    .vgpr_count:     256
    .vgpr_spill_count: 0
    .wavefront_size: 64
